# retention items renumbered so retkv producers and retout consumers of one (batch,head) share an XCD; retkv->mix barriers (phases 4, 9) XCD-local; dead third-item chain removed
# speedup vs baseline: 1.0119x; 1.0119x over previous
.LBB0_611:
	s_andn2_b64 vcc, exec, s[4:5]
	s_cbranch_vccnz .LBB0_613
	s_lshr_b32 s2, s8, 2
	s_and_b32 s2, s2, 14
	s_add_i32 s9, s9, 14
	s_or_b32 s2, s2, s9
	s_and_b32 s2, s2, 15
	s_and_b32 s4, s8, 7
	s_lshl_b32 s4, s4, 2
	s_lshr_b32 s3, s8, 6
	s_add_i32 s4, s4, s3
	s_mul_i32 s4, s4, 18
	s_mov_b32 s3, 3
	s_add_i32 s2, s2, s4

.Lg1_xc:
	s_cmpk_lt_i32 s73, 0xc0
	s_cbranch_scc0 .Lg1_xnone
	s_sub_i32 s2, s73, 0x80
	s_and_b32 s4, s2, 7
	s_lshl_b32 s4, s4, 2
	s_lshr_b32 s3, s2, 4
	s_add_i32 s4, s4, s3
	s_mul_i32 s4, s4, 18
	s_lshr_b32 s2, s2, 3
	s_and_b32 s2, s2, 1
	s_or_b32 s2, s4, s2
	s_add_i32 s2, s2, 16
	s_mov_b32 s3, 3

.LBB0_621:
.Lg1_none:
	s_mov_b32 s10, 17
	s_mov_b32 s2, 0
	s_mov_b32 s3, -1
	s_and_b64 vcc, exec, s[0:1]
	s_cbranch_vccnz .LBB0_25

.LBB0_631:
	v_sub_u32_e32 v10, 0x7f, v57
	v_cvt_f32_i32_e32 v10, v10
	v_cvt_f32_i32_e32 v11, v57
	v_lshlrev_b32_e32 v12, 6, v57
	v_bfe_u32 v14, v58, 2, 3
	v_mul_f32_e64 v10, -v56, v10
	v_mul_f32_e32 v10, 0x3fb8aa3b, v10
	v_exp_f32_e32 v10, v10
	v_mul_f32_e64 v11, -v53, v11
	s_movk_i32 s0, 0xf000
	v_and_b32_e32 v15, 56, v57
	v_mul_f32_e32 v11, 0x3fb8aa3b, v11
	v_and_or_b32 v12, v12, s0, v14
	v_bitop3_b32 v15, v15, v50, v52 bitop3:0xde
	v_exp_f32_e32 v11, v11
	v_mul_f32_e32 v14, v10, v28
	v_or_b32_e32 v17, v15, v12
	v_cvt_pk_bf16_f32 v14, v14, s0
	v_lshl_add_u32 v17, v17, 1, 0
	ds_write_b16 v17, v14 offset:16384
	v_mul_f32_e32 v14, v10, v4
	v_add_u32_e32 v15, v12, v15
	v_cvt_pk_bf16_f32 v14, v14, s0
	v_lshl_add_u32 v15, v15, 1, 0
	ds_write_b16 v15, v14 offset:18432
	v_mul_f32_e32 v14, v11, v28
	v_mul_f32_e32 v4, v11, v4
	v_bitop3_b32 v16, v57, v52, 56 bitop3:0x6c
	v_cvt_pk_bf16_f32 v14, v14, s0
	v_cvt_pk_bf16_f32 v4, v4, s0
	ds_write_b16 v17, v14 offset:32768
	ds_write_b16 v15, v4 offset:34816
	v_mul_f32_e32 v4, v10, v29
	v_add3_u32 v14, v50, v16, v12
	v_cvt_pk_bf16_f32 v4, v4, s0
	v_lshl_add_u32 v14, v14, 1, 0
	ds_write_b16 v14, v4 offset:16512
	v_mul_f32_e32 v4, v10, v5
	v_cvt_pk_bf16_f32 v4, v4, s0
	ds_write_b16 v14, v4 offset:18560
	v_mul_f32_e32 v4, v11, v29
	v_lshrrev_b32_e32 v13, 3, v57
	v_cvt_pk_bf16_f32 v4, v4, s0
	ds_write_b16 v14, v4 offset:32896
	v_mul_f32_e32 v4, v11, v5
	v_xor_b32_e32 v5, v49, v13
	v_lshlrev_b32_e32 v5, 3, v5
	v_cvt_pk_bf16_f32 v4, v4, s0
	v_and_or_b32 v5, v5, 56, v48
	ds_write_b16 v14, v4 offset:34944
	v_mul_f32_e32 v4, v10, v26
	v_or_b32_e32 v14, v5, v12
	v_cvt_pk_bf16_f32 v4, v4, s0
	v_lshl_add_u32 v14, v14, 1, 0
	ds_write_b16 v14, v4 offset:16384
	v_mul_f32_e32 v4, v10, v6
	v_add_u32_e32 v5, v5, v12
	v_cvt_pk_bf16_f32 v4, v4, s0
	v_lshl_add_u32 v5, v5, 1, 0
	ds_write_b16 v5, v4 offset:18432
	v_mul_f32_e32 v4, v11, v26
	v_cvt_pk_bf16_f32 v4, v4, s0
	ds_write_b16 v14, v4 offset:32768
	v_mul_f32_e32 v4, v11, v6
	v_cvt_pk_bf16_f32 v4, v4, s0
	ds_write_b16 v5, v4 offset:34816
	v_xor_b32_e32 v5, v47, v13
	v_lshlrev_b32_e32 v5, 3, v5
	v_and_or_b32 v5, v5, 56, v46
	v_mul_f32_e32 v4, v10, v27
	v_or_b32_e32 v6, v5, v12
	v_cvt_pk_bf16_f32 v4, v4, s0
	v_lshl_add_u32 v6, v6, 1, 0
	ds_write_b16 v6, v4 offset:16384
	v_mul_f32_e32 v4, v10, v7
	v_add_u32_e32 v5, v5, v12
	v_cvt_pk_bf16_f32 v4, v4, s0
	v_lshl_add_u32 v5, v5, 1, 0
	ds_write_b16 v5, v4 offset:18432
	v_mul_f32_e32 v4, v11, v27
	v_cvt_pk_bf16_f32 v4, v4, s0
	ds_write_b16 v6, v4 offset:32768
	v_mul_f32_e32 v4, v11, v7
	v_cvt_pk_bf16_f32 v4, v4, s0
	ds_write_b16 v5, v4 offset:34816
	v_xor_b32_e32 v5, v44, v13
	v_lshlrev_b32_e32 v5, 3, v5
	v_and_or_b32 v5, v5, 56, v43
	v_mul_f32_e32 v4, v10, v22
	v_or_b32_e32 v6, v5, v12
	v_cvt_pk_bf16_f32 v4, v4, s0
	v_lshl_add_u32 v6, v6, 1, 0
	ds_write_b16 v6, v4 offset:16384
	v_mul_f32_e32 v4, v10, v8
	v_add_u32_e32 v5, v5, v12
	v_cvt_pk_bf16_f32 v4, v4, s0
	v_lshl_add_u32 v5, v5, 1, 0
	ds_write_b16 v5, v4 offset:18432
	v_mul_f32_e32 v4, v11, v22
	v_cvt_pk_bf16_f32 v4, v4, s0
	ds_write_b16 v6, v4 offset:32768
	v_mul_f32_e32 v4, v11, v8
	v_cvt_pk_bf16_f32 v4, v4, s0
	ds_write_b16 v5, v4 offset:34816
	v_xor_b32_e32 v5, v42, v13
	v_lshlrev_b32_e32 v5, 3, v5
	v_and_or_b32 v5, v5, 56, v41
	v_mul_f32_e32 v4, v10, v23
	v_or_b32_e32 v6, v5, v12
	v_cvt_pk_bf16_f32 v4, v4, s0
	v_lshl_add_u32 v6, v6, 1, 0
	ds_write_b16 v6, v4 offset:16384
	v_mul_f32_e32 v4, v10, v9
	v_add_u32_e32 v5, v5, v12
	v_cvt_pk_bf16_f32 v4, v4, s0
	v_lshl_add_u32 v5, v5, 1, 0
	ds_write_b16 v5, v4 offset:18432
	v_mul_f32_e32 v4, v11, v23
	v_cvt_pk_bf16_f32 v4, v4, s0
	ds_write_b16 v6, v4 offset:32768
	v_mul_f32_e32 v4, v11, v9
	v_cvt_pk_bf16_f32 v4, v4, s0
	ds_write_b16 v5, v4 offset:34816
	v_xor_b32_e32 v5, v40, v13
	v_lshlrev_b32_e32 v5, 3, v5
	v_and_or_b32 v5, v5, 56, v38
	v_mul_f32_e32 v4, v10, v20
	v_or_b32_e32 v6, v5, v12
	v_cvt_pk_bf16_f32 v4, v4, s0
	v_lshl_add_u32 v6, v6, 1, 0
	ds_write_b16 v6, v4 offset:16384
	v_mul_f32_e32 v4, v10, v59
	v_add_u32_e32 v5, v5, v12
	v_cvt_pk_bf16_f32 v4, v4, s0
	v_lshl_add_u32 v5, v5, 1, 0
	ds_write_b16 v5, v4 offset:18432
	v_mul_f32_e32 v4, v11, v20
	v_cvt_pk_bf16_f32 v4, v4, s0
	ds_write_b16 v6, v4 offset:32768
	v_mul_f32_e32 v4, v11, v59
	v_cvt_pk_bf16_f32 v4, v4, s0
	ds_write_b16 v5, v4 offset:34816
	v_xor_b32_e32 v5, v33, v13
	v_lshlrev_b32_e32 v5, 3, v5
	v_and_or_b32 v5, v5, 56, v32
	v_mul_f32_e32 v4, v10, v21
	v_or_b32_e32 v6, v5, v12
	v_mul_f32_e32 v3, 0x3e000000, v3
	v_cvt_pk_bf16_f32 v4, v4, s0
	v_lshl_add_u32 v6, v6, 1, 0
	ds_write_b16 v6, v4 offset:16384
	v_mul_f32_e32 v4, v10, v3
	v_add_u32_e32 v5, v5, v12
	v_cvt_pk_bf16_f32 v4, v4, s0
	v_lshl_add_u32 v5, v5, 1, 0
	v_lshrrev_b32_e32 v2, 4, v34
	s_ashr_i32 s4, s7, 6
	ds_write_b16 v5, v4 offset:18432
	v_mul_f32_e32 v4, v11, v21
	v_mul_f32_e32 v3, v11, v3
	v_bfe_u32 v31, v34, 1, 3
	v_and_b32_e32 v0, 15, v34
	v_cvt_pk_bf16_f32 v4, v4, s0
	v_cvt_pk_bf16_f32 v3, v3, s0
	s_lshl_b32 s0, s4, 11
	v_bitop3_b32 v2, v2, v31, 3 bitop3:0x6c
	ds_write_b16 v6, v4 offset:32768
	v_lshlrev_b32_e32 v40, 7, v0
	v_lshlrev_b32_e32 v6, 4, v2
	s_add_i32 s0, s0, 0
	v_add3_u32 v48, s0, v6, v40
	ds_write_b16 v5, v3 offset:34816
	s_waitcnt lgkmcnt(0)
	s_barrier
	ds_read_b128 v[2:5], v48
	v_or_b32_e32 v6, v6, v40
	v_add_u32_e32 v52, 0, v6
	v_bfe_u32 v30, v34, 4, 2
	ds_read_b128 v[6:9], v52 offset:16384
	ds_read_b128 v[10:13], v52 offset:32768
	ds_read_b128 v[14:17], v52 offset:18432
	ds_read_b128 v[18:21], v52 offset:34816
	ds_read_b128 v[22:25], v52 offset:20480
	ds_read_b128 v[26:29], v52 offset:36864
	ds_read_b128 v[32:35], v52 offset:22528
	ds_read_b128 v[36:39], v52 offset:38912
	v_bitop3_b32 v31, v30, v31, 4 bitop3:0x36
	v_lshlrev_b32_e32 v31, 4, v31
	v_add3_u32 v53, s0, v31, v40
	s_waitcnt lgkmcnt(7)
	v_mfma_f32_16x16x32_bf16 v[6:9], v[2:5], v[6:9], 0
	v_or_b32_e32 v31, v31, v40
	v_add_u32_e32 v31, 0, v31
	s_ashr_i32 s7, s6, 31
	s_waitcnt lgkmcnt(6)
	v_mfma_f32_16x16x32_bf16 v[10:13], v[2:5], v[10:13], 0
	s_lshl_b64 s[0:1], s[6:7], 15
	s_add_u32 s0, s89, s0
	s_addc_u32 s1, s91, s1
	s_waitcnt lgkmcnt(5)
	v_mfma_f32_16x16x32_bf16 v[14:17], v[2:5], v[14:17], 0
	s_mov_b32 s6, s100
	s_lshl_b32 s13, s100, 7
	s_add_i32 s6, s6, s80
	s_add_i32 s13, s13, s12
	s_cmpk_gt_i32 s6, 0x23f
	s_waitcnt lgkmcnt(4)
	v_mfma_f32_16x16x32_bf16 v[18:21], v[2:5], v[18:21], 0
	s_waitcnt lgkmcnt(3)
	v_mfma_f32_16x16x32_bf16 v[22:25], v[2:5], v[22:25], 0
	s_waitcnt lgkmcnt(2)
	v_mfma_f32_16x16x32_bf16 v[26:29], v[2:5], v[26:29], 0
	s_waitcnt lgkmcnt(1)
	v_mfma_f32_16x16x32_bf16 v[32:35], v[2:5], v[32:35], 0
	s_waitcnt lgkmcnt(0)
	v_mfma_f32_16x16x32_bf16 v[2:5], v[2:5], v[36:39], 0
	ds_read_b128 v[36:39], v53
	ds_read_b128 v[40:43], v31 offset:16384
	ds_read_b128 v[44:47], v31 offset:32768
	s_waitcnt lgkmcnt(1)
	v_mfma_f32_16x16x32_bf16 v[6:9], v[36:39], v[40:43], v[6:9]
	s_waitcnt lgkmcnt(0)
	v_mfma_f32_16x16x32_bf16 v[10:13], v[36:39], v[44:47], v[10:13]
	ds_read_b128 v[40:43], v31 offset:18432
	ds_read_b128 v[44:47], v31 offset:34816
	s_waitcnt lgkmcnt(1)
	v_mfma_f32_16x16x32_bf16 v[14:17], v[36:39], v[40:43], v[14:17]
	s_waitcnt lgkmcnt(0)
	v_mfma_f32_16x16x32_bf16 v[18:21], v[36:39], v[44:47], v[18:21]
	ds_read_b128 v[40:43], v31 offset:20480
	ds_read_b128 v[44:47], v31 offset:36864
	s_waitcnt lgkmcnt(1)
	v_mfma_f32_16x16x32_bf16 v[40:43], v[36:39], v[40:43], v[22:25]
	s_waitcnt lgkmcnt(0)
	v_mfma_f32_16x16x32_bf16 v[26:29], v[36:39], v[44:47], v[26:29]
	s_nop 0
	ds_read_b128 v[22:25], v31 offset:22528
	ds_read_b128 v[44:47], v31 offset:38912
	s_waitcnt lgkmcnt(1)
	v_mfma_f32_16x16x32_bf16 v[32:35], v[36:39], v[22:25], v[32:35]
	s_waitcnt lgkmcnt(0)
	v_mfma_f32_16x16x32_bf16 v[2:5], v[36:39], v[44:47], v[2:5]
	ds_read_b128 v[36:39], v48 offset:8192
	ds_read_b128 v[22:25], v52 offset:24576
	ds_read_b128 v[44:47], v52 offset:40960
	s_waitcnt lgkmcnt(1)
	v_mfma_f32_16x16x32_bf16 v[48:51], v[36:39], v[22:25], v[6:9]
	s_waitcnt lgkmcnt(0)
	v_mfma_f32_16x16x32_bf16 v[44:47], v[36:39], v[44:47], v[10:13]
	s_nop 0
	ds_read_b128 v[6:9], v52 offset:26624
	s_nop 0
	ds_read_b128 v[10:13], v52 offset:43008
	s_waitcnt lgkmcnt(1)
	v_mfma_f32_16x16x32_bf16 v[22:25], v[36:39], v[6:9], v[14:17]
	s_waitcnt lgkmcnt(0)
	v_mfma_f32_16x16x32_bf16 v[10:13], v[36:39], v[10:13], v[18:21]
	ds_read_b128 v[6:9], v52 offset:28672
	s_nop 1
	ds_read_b128 v[18:21], v52 offset:45056
	s_waitcnt lgkmcnt(1)
	v_mfma_f32_16x16x32_bf16 v[14:17], v[36:39], v[6:9], v[40:43]
	s_waitcnt lgkmcnt(0)
	v_mfma_f32_16x16x32_bf16 v[18:21], v[36:39], v[18:21], v[26:29]
	ds_read_b128 v[6:9], v52 offset:30720
	s_nop 1
	ds_read_b128 v[26:29], v52 offset:47104
	s_waitcnt lgkmcnt(1)
	v_mfma_f32_16x16x32_bf16 v[6:9], v[36:39], v[6:9], v[32:35]
	s_waitcnt lgkmcnt(0)
	v_mfma_f32_16x16x32_bf16 v[2:5], v[36:39], v[26:29], v[2:5]
	ds_read_b128 v[26:29], v53 offset:8192
	ds_read_b128 v[32:35], v31 offset:24576
	ds_read_b128 v[36:39], v31 offset:40960
	s_waitcnt lgkmcnt(0)
	v_mfma_f32_16x16x32_bf16 v[36:39], v[26:29], v[36:39], v[44:47]
	ds_read_b128 v[40:43], v31 offset:26624
	s_nop 1
	ds_read_b128 v[44:47], v31 offset:43008
	s_waitcnt lgkmcnt(1)
	v_mfma_f32_16x16x32_bf16 v[22:25], v[26:29], v[40:43], v[22:25]
	s_waitcnt lgkmcnt(0)
	v_mfma_f32_16x16x32_bf16 v[10:13], v[26:29], v[44:47], v[10:13]
	ds_read_b128 v[40:43], v31 offset:28672
	ds_read_b128 v[44:47], v31 offset:45056
	s_waitcnt lgkmcnt(1)
	v_mfma_f32_16x16x32_bf16 v[14:17], v[26:29], v[40:43], v[14:17]
	s_waitcnt lgkmcnt(0)
	v_mfma_f32_16x16x32_bf16 v[18:21], v[26:29], v[44:47], v[18:21]
	ds_read_b128 v[40:43], v31 offset:30720
	ds_read_b128 v[44:47], v31 offset:47104
	v_mfma_f32_16x16x32_bf16 v[32:35], v[26:29], v[32:35], v[48:51]
	s_waitcnt lgkmcnt(1)
	v_mfma_f32_16x16x32_bf16 v[6:9], v[26:29], v[40:43], v[6:9]
	s_waitcnt lgkmcnt(0)
	v_mfma_f32_16x16x32_bf16 v[2:5], v[26:29], v[44:47], v[2:5]
	v_lshlrev_b32_e32 v26, 8, v30
	v_lshl_or_b32 v40, s4, 10, v26
	v_or_b32_e32 v26, v40, v0
	v_ashrrev_i32_e32 v27, 31, v26
	v_lshl_add_u64 v[28:29], v[26:27], 2, s[0:1]
	v_ashrrev_i32_e32 v27, 31, v40
	v_or_b32_e32 v30, 16, v26
	v_mov_b32_e32 v31, v27
	global_store_dword v[28:29], v32, off
	v_lshl_add_u64 v[28:29], v[26:27], 2, s[0:1]
	v_lshl_add_u64 v[30:31], v[30:31], 2, s[0:1]
	global_store_dword v[28:29], v33, off offset:256
	global_store_dword v[28:29], v34, off offset:512
	global_store_dword v[28:29], v35, off offset:768
	global_store_dword v[28:29], v22, off offset:64
	global_store_dword v[30:31], v23, off offset:256
	global_store_dword v[30:31], v24, off offset:512
	global_store_dword v[30:31], v25, off offset:768
	global_store_dword v[28:29], v14, off offset:128
	v_or_b32_e32 v22, 32, v26
	v_mov_b32_e32 v23, v27
	v_lshl_add_u64 v[22:23], v[22:23], 2, s[0:1]
	v_or_b32_e32 v26, 48, v26
	global_store_dword v[22:23], v15, off offset:256
	global_store_dword v[22:23], v16, off offset:512
	global_store_dword v[22:23], v17, off offset:768
	global_store_dword v[28:29], v6, off offset:192
	v_lshl_add_u64 v[14:15], v[26:27], 2, s[0:1]
	global_store_dword v[14:15], v7, off offset:256
	global_store_dword v[14:15], v8, off offset:512
	global_store_dword v[14:15], v9, off offset:768
	v_or_b32_e32 v8, 0x1000, v0
	v_add_u32_e32 v6, v40, v8
	v_ashrrev_i32_e32 v7, 31, v6
	v_or_b32_e32 v32, 64, v40
	v_lshl_add_u64 v[6:7], v[6:7], 2, s[0:1]
	global_store_dword v[6:7], v36, off
	v_add_u32_e32 v6, v32, v8
	v_ashrrev_i32_e32 v7, 31, v6
	v_or_b32_e32 v33, 0x80, v40
	v_lshl_add_u64 v[6:7], v[6:7], 2, s[0:1]
	global_store_dword v[6:7], v37, off
	v_add_u32_e32 v6, v33, v8
	v_ashrrev_i32_e32 v7, 31, v6
	v_or_b32_e32 v34, 0xc0, v40
	v_lshl_add_u64 v[6:7], v[6:7], 2, s[0:1]
	global_store_dword v[6:7], v38, off
	v_add_u32_e32 v6, v34, v8
	v_ashrrev_i32_e32 v7, 31, v6
	v_lshl_add_u64 v[6:7], v[6:7], 2, s[0:1]
	v_or_b32_e32 v8, 0x1010, v0
	global_store_dword v[6:7], v39, off
	v_add_u32_e32 v6, v40, v8
	v_ashrrev_i32_e32 v7, 31, v6
	v_lshl_add_u64 v[6:7], v[6:7], 2, s[0:1]
	global_store_dword v[6:7], v10, off
	v_add_u32_e32 v6, v32, v8
	v_ashrrev_i32_e32 v7, 31, v6
	v_lshl_add_u64 v[6:7], v[6:7], 2, s[0:1]
	global_store_dword v[6:7], v11, off
	v_add_u32_e32 v6, v33, v8
	v_ashrrev_i32_e32 v7, 31, v6
	v_lshl_add_u64 v[6:7], v[6:7], 2, s[0:1]
	global_store_dword v[6:7], v12, off
	v_add_u32_e32 v6, v34, v8
	v_ashrrev_i32_e32 v7, 31, v6
	v_lshl_add_u64 v[6:7], v[6:7], 2, s[0:1]
	v_or_b32_e32 v8, 0x1020, v0
	global_store_dword v[6:7], v13, off
	v_add_u32_e32 v6, v40, v8
	v_ashrrev_i32_e32 v7, 31, v6
	v_lshl_add_u64 v[6:7], v[6:7], 2, s[0:1]
	global_store_dword v[6:7], v18, off
	v_add_u32_e32 v6, v32, v8
	v_ashrrev_i32_e32 v7, 31, v6
	v_lshl_add_u64 v[6:7], v[6:7], 2, s[0:1]
	global_store_dword v[6:7], v19, off
	v_add_u32_e32 v6, v33, v8
	v_ashrrev_i32_e32 v7, 31, v6
	v_lshl_add_u64 v[6:7], v[6:7], 2, s[0:1]
	global_store_dword v[6:7], v20, off
	v_add_u32_e32 v6, v34, v8
	v_ashrrev_i32_e32 v7, 31, v6
	v_lshl_add_u64 v[6:7], v[6:7], 2, s[0:1]
	v_or_b32_e32 v0, 0x1030, v0
	global_store_dword v[6:7], v21, off
	v_add_u32_e32 v6, v40, v0
	v_ashrrev_i32_e32 v7, 31, v6
	v_lshl_add_u64 v[6:7], v[6:7], 2, s[0:1]
	global_store_dword v[6:7], v2, off
	v_add_u32_e32 v6, v32, v0
	v_ashrrev_i32_e32 v7, 31, v6
	v_lshl_add_u64 v[6:7], v[6:7], 2, s[0:1]
	v_add_u32_e32 v2, v33, v0
	global_store_dword v[6:7], v3, off
	v_ashrrev_i32_e32 v3, 31, v2
	v_lshl_add_u64 v[2:3], v[2:3], 2, s[0:1]
	global_store_dword v[2:3], v4, off
	v_add_u32_e32 v2, v34, v0
	v_ashrrev_i32_e32 v3, 31, v2
	v_lshl_add_u64 v[2:3], v[2:3], 2, s[0:1]
	global_store_dword v[2:3], v5, off
	s_barrier
	s_cbranch_scc1 .LBB0_644
.LBB0_632:
	s_mov_b32 s100, s6
	s_and_b32 s0, s6, 7
	s_lshl_b32 s0, s0, 2
	s_cmpk_lt_i32 s6, 0x200
	s_cbranch_scc0 .Lrk_hi
	s_lshr_b32 s1, s6, 7
	s_add_i32 s0, s0, s1
	s_bfe_u32 s1, s6, 0x40003
	s_branch .Lrk_go
.Lrk_hi:
	s_bfe_u32 s1, s6, 0x20004
	s_add_i32 s0, s0, s1
	s_bfe_u32 s1, s6, 0x10003
	s_add_i32 s1, s1, 16
.Lrk_go:
	s_mul_i32 s0, s0, 18
	s_add_i32 s6, s0, s1
	s_lshl_b32 s13, s6, 7
	s_mul_hi_i32 s0, s6, 0x38e38e39
	s_lshr_b32 s1, s0, 31
	s_ashr_i32 s9, s0, 2
	s_add_i32 s9, s9, s1
	s_mul_i32 s0, s9, 0xffffffee
	s_add_i32 s0, s6, s0
	s_ashr_i32 s10, s9, 2
	s_cmp_gt_i32 s0, 15
	v_mov_b32_e32 v34, v175
	s_cselect_b64 s[0:1], -1, 0
	s_mov_b64 s[4:5], -1
	v_readfirstlane_b32 s7, v34
	s_and_b64 vcc, exec, s[0:1]
	s_cbranch_vccz .LBB0_634
	s_mul_i32 s4, s9, 18
	s_sub_i32 s4, s6, s4
	s_lshl_b32 s4, s4, 7
	s_lshl_b32 s5, s10, 8
	s_add_i32 s4, s4, s5
	s_add_i32 s8, s4, 0x3800
	s_mov_b64 s[4:5], 0

.LBB0_948:
	s_mov_b64 s[2:3], exec
	s_cmp_eq_u32 s76, 2
	s_cbranch_scc1 .Lxb_maybe_local
	s_cmp_eq_u32 s76, 4
	s_cbranch_scc1 .Lxb_maybe_local
	s_cmp_eq_u32 s76, 9
	s_cbranch_scc1 .Lxb_maybe_local
	s_cmp_eq_u32 s76, 6
	s_cbranch_scc1 .Lxb_maybe_local
	s_cmp_eq_u32 s76, 7
	s_cbranch_scc0 .Lxb_global
